# mixer prompt band attention: V block prefetched one iteration ahead (into the registers just staged to LDS) instead of loaded at the top of its own iteration
# baseline (speedup 1.0000x reference)
; #define LAS __attribute__((address_space(3)))
; __device__ __forceinline__ void band_attn_p2(const Params& P, int l, int b, int c, int h, LAS unsigned char* wl, int lane_) {
;     int lane = lane_; asm volatile("" : "+v"(lane));
;     const int r = lane & 31, hi = lane >> 5;
;     LAS float* tab = (LAS float*)wl;
;     LAS unsigned char* vst = wl + 2048;
;     LAS unsigned char* kst = wl + 6144;
;     const bf16_t* Z = (const bf16_t*)(P.ws + WS_Z);
;     bf16_t* MIX = (bf16_t*)(P.ws + WS_MIX);
;     const float* rb = P.in[15] + (size_t)(l * 8 + h) * 257;
;     for (int i = lane; i < 257; i += 64) tab[i] = rb[i] * LOG2E;
;     const int qrow0 = b * SEQ + c * 64;
;     bf16x8 qf[2][4];
;     AttnState st[2];
; #pragma unroll
;     for (int qb = 0; qb < 2; ++qb) {
; #pragma unroll
;         for (int d0 = 0; d0 < 4; ++d0) qf[qb][d0] = *(const bf16x8*)(Z + (size_t)(qrow0 + 32 * qb + r) * DIN + h * 64 + 16 * d0 + 8 * hi);
;         st[qb].mrun = -1e30f; st[qb].lsum = 0.f;
; #pragma unroll
;         for (int db = 0; db < 2; ++db)
; #pragma unroll
;             for (int e = 0; e < 16; ++e) st[qb].O[db][e] = 0.f;
;     }
;     const float tconst = tab[256];
;     const int vr0 = lane >> 3, vch = lane & 7;
;     const int jb0 = c < 8 ? (8 - c) * 2 : 0;
;     const bf16_t* zb = Z + (size_t)(b * SEQ + (c - 8) * 64 + vr0) * DIN + h * 64 + 8 * vch;
;     bf16x8 kc[4], kn[4], vc[4];
; #pragma unroll
;     for (int i = 0; i < 4; ++i) kc[i] = *(const bf16x8*)(zb + (size_t)(32 * jb0 + 8 * i) * DIN + 512);
.LBB0_694:
	s_or_b64 exec, exec, s[0:1]
	s_ashr_i32 s52, s50, 7
	s_and_b32 s8, s50, 0x7f
	v_ashrrev_i32_e32 v10, 5, v2
	s_lshl_b32 s5, s52, 13
	s_lshl_b32 s36, s8, 6
	v_and_b32_e32 v3, 31, v2
	s_or_b32 s37, s36, s5
	v_lshlrev_b32_e32 v190, 3, v10
	v_or_b32_e32 v188, s37, v3
	v_ashrrev_i32_e32 v191, 31, v190
	s_and_b32 s0, s69, 0x7f
	v_lshl_add_u64 v[6:7], v[190:191], 1, s[40:41]
	v_or_b32_e32 v186, 32, v188
	s_lshl_b32 s4, s0, 6
	v_mad_i64_i32 v[8:9], s[0:1], v188, s66, v[6:7]
	v_mad_i64_i32 v[6:7], s[0:1], v186, s66, v[6:7]
	s_lshl_b32 s0, s8, 1
	s_sub_i32 s0, 16, s0
	s_cmp_lt_u32 s8, 8
	global_load_dwordx4 v[98:101], v[8:9], off
	global_load_dwordx4 v[102:105], v[8:9], off offset:32
	global_load_dwordx4 v[106:109], v[8:9], off offset:64
	global_load_dwordx4 v[110:113], v[8:9], off offset:96
	v_mov_b32_e32 v0, s44
	v_ashrrev_i32_e32 v192, 3, v2
	s_cselect_b32 s6, s0, 0
	s_add_i32 s0, s37, 0xfffffe00
	v_lshlrev_b32_e32 v8, 3, v2
	v_mov_b64_e32 v[4:5], s[40:41]
	global_load_dwordx4 v[114:117], v[6:7], off
	global_load_dwordx4 v[118:121], v[6:7], off offset:32
	global_load_dwordx4 v[122:125], v[6:7], off offset:64
	global_load_dwordx4 v[126:129], v[6:7], off offset:96
	ds_read_b32 v194, v0 offset:1024
	v_add_u32_e32 v0, s0, v192
	v_and_b32_e32 v196, 56, v8
	v_mad_i64_i32 v[4:5], s[0:1], v0, s66, v[4:5]
	v_lshlrev_b32_e32 v0, 1, v196
	v_lshl_add_u64 v[4:5], v[4:5], 0, v[0:1]
	s_mul_i32 s62, s6, 0x28000
	v_lshl_add_u64 v[4:5], v[4:5], 0, s[62:63]
	s_mov_b32 s0, 0xa000
	v_add_co_u32_e32 v6, vcc, s0, v4
	s_mov_b32 s0, 0x14000
	s_nop 0
	v_addc_co_u32_e32 v7, vcc, 0, v5, vcc
	global_load_dwordx4 v[66:69], v[4:5], off offset:1024
	global_load_dwordx4 v[70:73], v[6:7], off offset:1024
	v_add_co_u32_e32 v6, vcc, s0, v4
	s_mov_b32 s0, 0x1e000
	s_nop 0
	v_addc_co_u32_e32 v7, vcc, 0, v5, vcc
	v_add_co_u32_e32 v4, vcc, s0, v4
	v_lshrrev_b32_e32 v0, 1, v192
	s_nop 0
	v_addc_co_u32_e32 v5, vcc, 0, v5, vcc
	global_load_dwordx4 v[74:77], v[6:7], off offset:1024
	global_load_dwordx4 v[78:81], v[4:5], off offset:1024
	v_xor_b32_e32 v0, v0, v2
	v_lshlrev_b32_e32 v0, 4, v0
	v_and_b32_e32 v0, 0x70, v0
	v_add_u32_e32 v17, s44, v0
	v_add_u32_e32 v0, 8, v192
	v_lshrrev_b32_e32 v4, 1, v0
	v_xor_b32_e32 v4, v4, v2
	v_lshlrev_b32_e32 v4, 4, v4
	v_and_b32_e32 v4, 0x70, v4
	v_add_u32_e32 v19, s44, v4
	v_add_u32_e32 v4, 24, v192
	v_lshrrev_b32_e32 v5, 1, v4
	v_xor_b32_e32 v5, v5, v2
	v_lshlrev_b32_e32 v5, 4, v5
	v_and_b32_e32 v5, 0x70, v5
	v_add_u32_e32 v21, s44, v5
	v_lshlrev_b32_e32 v5, 7, v2
	v_and_b32_e32 v5, 0xf80, v5
	v_lshrrev_b32_e32 v6, 1, v2
	v_add_u32_e32 v22, s44, v5
	v_bitop3_b32 v5, v6, v10, 7 bitop3:0x6c
	v_lshlrev_b32_e32 v23, 4, v5
	v_add_u32_e32 v5, 2, v10
	v_bitop3_b32 v5, v5, v6, 7 bitop3:0x78
	v_lshlrev_b32_e32 v24, 4, v5
	v_add_u32_e32 v5, 4, v10
	v_bitop3_b32 v5, v5, v6, 7 bitop3:0x78
	v_lshlrev_b32_e32 v25, 4, v5
	v_add_u32_e32 v5, 6, v10
	v_bitop3_b32 v5, v5, v6, 7 bitop3:0x78
	v_and_b32_e32 v6, 64, v210
	v_lshlrev_b32_e32 v26, 4, v5
	v_xor_b32_e32 v5, 32, v210
	v_add_u32_e32 v206, 64, v6
	v_cmp_lt_i32_e32 vcc, v5, v206
	v_lshlrev_b32_e32 v18, 7, v0
	v_lshlrev_b32_e32 v7, 6, v192
	v_cndmask_b32_e32 v5, v210, v5, vcc
	v_lshlrev_b32_e32 v201, 2, v5
	v_bfe_u32 v5, v8, 5, 1
	v_lshlrev_b32_e32 v8, 4, v2
	s_mov_b32 s0, 0x7ffffe
	v_lshrrev_b32_e32 v0, 2, v0
	v_and_b32_e32 v7, 0x1c0, v7
	v_and_b32_e32 v9, 48, v8
	v_and_or_b32 v0, v0, s0, v5
	v_add3_u32 v27, s44, v7, v9
	v_and_b32_e32 v7, 16, v2
	v_lshlrev_b32_e32 v9, 2, v2
	v_lshlrev_b32_e32 v30, 9, v0
	v_add_u32_e32 v0, 16, v192
	v_and_or_b32 v7, v9, 12, v7
	v_lshlrev_b32_e32 v9, 8, v10
	v_lshrrev_b32_e32 v0, 2, v0
	v_and_b32_e32 v9, 0x100, v9
	v_and_or_b32 v0, v0, s0, v5
	v_and_b32_e32 v8, 0xc0, v8
	v_lshlrev_b32_e32 v7, 1, v7
	v_add_u32_e32 v9, s44, v9
	v_lshlrev_b32_e32 v31, 9, v0
	v_lshrrev_b32_e32 v0, 2, v4
	v_add3_u32 v28, v9, v8, v7
	v_and_or_b32 v7, v10, s0, v5
	v_and_or_b32 v0, v0, s0, v5
	s_lshl_b32 s0, s6, 5
	v_lshlrev_b32_e32 v32, 9, v0
	v_lshlrev_b32_e32 v0, 9, v10
	s_sub_i32 s7, 0, s0
	s_or_b32 s0, s4, s5
	v_lshlrev_b32_e32 v20, 7, v4
	v_lshlrev_b32_e32 v29, 9, v7
	v_and_b32_e32 v33, 0xfffffc00, v0
	v_add_u32_e32 v4, 0x400, v0
	v_add_u32_e32 v5, 0x800, v0
	v_add_u32_e32 v7, 0xc00, v0
	v_or_b32_e32 v37, 0x200, v0
	v_add_u32_e32 v0, s0, v192
	v_add_u32_e32 v0, 0xfffffe00, v0
	v_and_b32_e32 v34, 0xfffffc00, v4
	v_and_b32_e32 v35, 0xfffffc00, v5
	s_waitcnt vmcnt(0)
; __device__ __forceinline__ void band_attn_p2(const Params& P, int l, int b, int c, int h, LAS unsigned char* wl, int lane_) {
;     ...
;     const int qrow0 = b * SEQ + c * 64;
;     bf16x8 qf[2][4];
;     AttnState st[2];
; #pragma unroll
;     for (int qb = 0; qb < 2; ++qb) {
; #pragma unroll
;         for (int d0 = 0; d0 < 4; ++d0) qf[qb][d0] = *(const bf16x8*)(Z + (size_t)(qrow0 + 32 * qb + r) * DIN + h * 64 + 16 * d0 + 8 * hi);
;         st[qb].mrun = -1e30f; st[qb].lsum = 0.f;
; #pragma unroll
;         for (int db = 0; db < 2; ++db)
; #pragma unroll
;             for (int e = 0; e < 16; ++e) st[qb].O[db][e] = 0.f;
;     }
;     const float tconst = tab[256];
;     const int vr0 = lane >> 3, vch = lane & 7;
;     const int jb0 = c < 8 ? (8 - c) * 2 : 0;
;     const bf16_t* zb = Z + (size_t)(b * SEQ + (c - 8) * 64 + vr0) * DIN + h * 64 + 8 * vch;
;     bf16x8 kc[4], kn[4], vc[4];
; #pragma unroll
;     for (int i = 0; i < 4; ++i) kc[i] = *(const bf16x8*)(zb + (size_t)(32 * jb0 + 8 * i) * DIN + 512);
;     for (int j = jb0; j < 18; ++j) {
; #pragma unroll
;         for (int i = 0; i < 4; ++i) vc[i] = *(const bf16x8*)(zb + (size_t)(32 * j + 8 * i) * DIN + 1024);
;         if (j + 1 < 18) {
	v_or_b32_e32 v38, 0x200, v4
	v_or_b32_e32 v39, 0x200, v5
	v_mad_i64_i32 v[4:5], s[0:1], v0, s66, 0
	v_mov_b32_e32 v0, 0x28000
	v_mad_u64_u32 v[4:5], s[0:1], s6, v0, v[4:5]
	v_and_b32_e32 v200, 7, v2
	v_readlane_b32 s0, v255, 13
	v_and_b32_e32 v6, -4, v192
	v_and_b32_e32 v36, 0xfffffc00, v7
	v_or_b32_e32 v40, 0x200, v7
	v_lshl_or_b32 v4, v200, 4, v4
	v_readlane_b32 s1, v255, 14
	v_mov_b32_e32 v14, v1
	v_mov_b32_e32 v15, v1
	v_lshlrev_b32_e32 v16, 7, v192
	v_lshl_add_u64 v[204:205], s[0:1], 0, v[4:5]
	v_sub_u32_e32 v193, v3, v6
	v_mov_b32_e32 v0, v1
	v_mov_b32_e32 v2, v1
	v_mov_b32_e32 v3, v1
	v_mov_b32_e32 v4, v1
	v_mov_b32_e32 v5, v1
	v_mov_b32_e32 v6, v1
	v_mov_b32_e32 v7, v1
	v_mov_b32_e32 v8, v1
	v_mov_b32_e32 v9, v1
	v_mov_b32_e32 v10, v1
	v_mov_b32_e32 v11, v1
	v_mov_b32_e32 v12, v1
	v_mov_b32_e32 v13, v1
	v_add_u32_e32 v231, v19, v18
	v_add_u32_e32 v232, v21, v20
	v_add_u32_e32 v233, v22, v23
	v_add_u32_e32 v234, v22, v24
	v_add_u32_e32 v235, v22, v25
	v_add_u32_e32 v236, v22, v26
	v_add_u32_e32 v237, v27, v29
	v_add_u32_e32 v238, v27, v30
	v_add_u32_e32 v239, v27, v31
	v_add_u32_e32 v240, v27, v32
	v_add_u32_e32 v241, v28, v33
	v_add_u32_e32 v242, v28, v34
	v_add_u32_e32 v243, v28, v35
	v_add_u32_e32 v244, v28, v36
	v_add_u32_e32 v245, v28, v37
	v_add_u32_e32 v246, v28, v38
	v_add_u32_e32 v247, v28, v39
	v_add_u32_e32 v248, v28, v40
	v_mov_b64_e32 v[64:65], v[14:15]
	v_mov_b64_e32 v[48:49], v[14:15]
	v_mov_b64_e32 v[32:33], v[14:15]
	v_add_u32_e32 v230, v17, v16
	v_mov_b64_e32 v[62:63], v[12:13]
	v_mov_b64_e32 v[60:61], v[10:11]
	v_mov_b64_e32 v[58:59], v[8:9]
	v_mov_b64_e32 v[56:57], v[6:7]
	v_mov_b64_e32 v[54:55], v[4:5]
	v_mov_b64_e32 v[52:53], v[2:3]
	v_mov_b64_e32 v[50:51], v[0:1]
	v_mov_b64_e32 v[46:47], v[12:13]
	v_mov_b64_e32 v[44:45], v[10:11]
	v_mov_b64_e32 v[42:43], v[8:9]
	v_mov_b64_e32 v[40:41], v[6:7]
	v_mov_b64_e32 v[38:39], v[4:5]
	v_mov_b64_e32 v[36:37], v[2:3]
	v_mov_b64_e32 v[34:35], v[0:1]
	v_mov_b64_e32 v[30:31], v[12:13]
	v_mov_b64_e32 v[28:29], v[10:11]
	v_mov_b64_e32 v[26:27], v[8:9]
	v_mov_b64_e32 v[24:25], v[6:7]
	v_mov_b64_e32 v[22:23], v[4:5]
	v_mov_b64_e32 v[20:21], v[2:3]
	v_mov_b64_e32 v[18:19], v[0:1]
	v_mov_b64_e32 v[16:17], v[14:15]
	v_ashrrev_i32_e32 v189, 31, v188
	v_ashrrev_i32_e32 v187, 31, v186
	s_waitcnt lgkmcnt(0)
	v_mov_b32_e32 v202, v194
	v_mov_b32_e32 v203, v194
	v_mov_b32_e32 v229, 0
	v_mov_b32_e32 v249, 0xf149f2ca
	v_mov_b64_e32 v[14:15], v[12:13]
	v_mov_b64_e32 v[12:13], v[10:11]
	v_mov_b64_e32 v[10:11], v[8:9]
	v_mov_b64_e32 v[8:9], v[6:7]
	v_mov_b64_e32 v[6:7], v[4:5]
	v_mov_b64_e32 v[4:5], v[2:3]
	v_mov_b64_e32 v[2:3], v[0:1]
	v_mov_b32_e32 v0, 0xf149f2ca
	v_mov_b32_e32 v207, 0
	s_mov_b32 s0, 0xfffbb000
	v_add_co_u32_e32 v82, vcc, s0, v204
	s_nop 1
	v_addc_co_u32_e32 v83, vcc, -1, v205, vcc
	v_add_co_u32_e32 v84, vcc, 0xfffc5000, v204
	s_nop 1
	v_addc_co_u32_e32 v85, vcc, -1, v205, vcc
	global_load_dwordx4 v[146:149], v[82:83], off offset:-3072
	global_load_dwordx4 v[150:153], v[84:85], off offset:-3072
	v_add_co_u32_e32 v82, vcc, 0xfffcf000, v204
	s_nop 1
	v_addc_co_u32_e32 v83, vcc, -1, v205, vcc
	v_add_co_u32_e32 v84, vcc, 0xfffd9000, v204
	s_nop 1
	v_addc_co_u32_e32 v85, vcc, -1, v205, vcc
	global_load_dwordx4 v[154:157], v[82:83], off offset:-3072
	global_load_dwordx4 v[158:161], v[84:85], off offset:-3072
.LBB0_695:
	s_cmpk_lg_i32 s7, 0xfde0
	s_cbranch_scc0 .LBB0_697
	v_add_co_u32_e32 v82, vcc, 0xfffe2000, v204
	s_nop 1
	v_addc_co_u32_e32 v83, vcc, -1, v205, vcc
	v_add_co_u32_e32 v84, vcc, 0xfffec000, v204
	s_nop 1
	v_addc_co_u32_e32 v85, vcc, -1, v205, vcc
	global_load_dwordx4 v[130:133], v[82:83], off
	global_load_dwordx4 v[134:137], v[84:85], off
	v_add_co_u32_e32 v82, vcc, 0xffff6000, v204
	s_nop 1
	v_addc_co_u32_e32 v83, vcc, -1, v205, vcc
	global_load_dwordx4 v[142:145], v[82:83], off
	global_load_dwordx4 v[138:141], v[204:205], off

; #define LAS __attribute__((address_space(3)))
; __device__ __forceinline__ int voff_band(int key, int d) { return ((key >> 3) * 2 + (d >> 5)) * 512 + (key & 7) * 64 + (d & 31) * 2; }
; __device__ __forceinline__ void band_attn_p2(const Params& P, int l, int b, int c, int h, LAS unsigned char* wl, int lane_) {
;     ...
;         for (int i = 0; i < 4; ++i) vc[i] = *(const bf16x8*)(zb + (size_t)(32 * j + 8 * i) * DIN + 1024);
;         if (j + 1 < 18) {
; #pragma unroll
;             for (int i = 0; i < 4; ++i) kn[i] = *(const bf16x8*)(zb + (size_t)(32 * (j + 1) + 8 * i) * DIN + 512);
;         }
;         bf16x8 kf[4], pf[2][2];
;         k_frags(kf, kc, kst, lane);
; #pragma unroll
;         for (int qb = 0; qb < 2; ++qb) attn_score(st[qb], pf[qb], kf, qf[qb], j, 32 * qb + r, false, tab, tconst, lane);
; #pragma unroll
;         for (int i = 0; i < 4; ++i) *(LAS bf16x8*)(vst + voff_band(vr0 + 8 * i, 8 * vch)) = vc[i];
;         const int trow = 4 * hi + ((lane & 15) >> 2), tcol = 16 * ((lane >> 4) & 1) + 4 * (lane & 3);
; #pragma unroll
;         for (int db = 0; db < 2; ++db)
; #pragma unroll
;             for (int s2 = 0; s2 < 2; ++s2) {
;                 const s16x4 a0 = tr_read(vst + voff_band(16 * s2 + trow, 32 * db + tcol));
;                 const s16x4 a1 = tr_read(vst + voff_band(16 * s2 + 8 + trow, 32 * db + tcol));
;                 const bf16x8 vf = (bf16x8){a0[0], a0[1], a0[2], a0[3], a1[0], a1[1], a1[2], a1[3]};
;                 __builtin_amdgcn_s_setprio(1);
; #pragma unroll
;                 for (int qb = 0; qb < 2; ++qb) st[qb].O[db] = __builtin_amdgcn_mfma_f32_32x32x16_bf16(vf, pf[qb][s2], st[qb].O[db], 0, 0, 0);
;                 __builtin_amdgcn_s_setprio(0);
;             }
; #pragma unroll
;         for (int i = 0; i < 4; ++i) kc[i] = kn[i];
.Lp2_vwait_done:
	ds_write_b128 v237, v[146:149] offset:2048
	ds_write_b128 v238, v[150:153] offset:2048
	ds_write_b128 v239, v[154:157] offset:2048
	ds_write_b128 v240, v[158:161] offset:2048
	v_add_f32_e32 v82, v78, v82
	v_cvt_pk_bf16_f32 v66, v66, v67
	v_cvt_pk_bf16_f32 v67, v68, v69
	v_cvt_pk_bf16_f32 v68, v70, v71
	v_cvt_pk_bf16_f32 v69, v72, v73
	ds_read_b64_tr_b16 v[70:71], v241 offset:2048
	ds_read_b64_tr_b16 v[72:73], v242 offset:2048
	v_add_f32_e32 v82, v79, v82
	v_add_f32_e32 v82, v80, v82
	v_add_f32_e32 v82, v81, v82
	s_add_i32 s0, s6, 1
	v_add_f32_e32 v207, v207, v82
	v_cvt_pk_bf16_f32 v74, v74, v75
	v_cvt_pk_bf16_f32 v75, v76, v77
	v_cvt_pk_bf16_f32 v76, v78, v79
	v_cvt_pk_bf16_f32 v77, v80, v81
	s_setprio 1
	s_waitcnt lgkmcnt(0)
	v_mfma_f32_32x32x16_bf16 v[50:65], v[70:73], v[166:169], v[50:65]
	v_mfma_f32_32x32x16_bf16 v[18:33], v[70:73], v[66:69], v[18:33]
	s_setprio 0
	s_cmpk_lg_i32 s7, 0xfde0
	s_cbranch_scc0 .Lp2_nov
	s_mov_b32 s3, -1
	s_mov_b32 s2, 0xfffe3000
	v_lshl_add_u64 v[148:149], v[204:205], 0, s[2:3]
	s_mov_b32 s2, 0xfffed000
	v_lshl_add_u64 v[152:153], v[204:205], 0, s[2:3]
	global_load_dwordx4 v[146:149], v[148:149], off offset:-3072
	global_load_dwordx4 v[150:153], v[152:153], off offset:-3072
	s_mov_b32 s2, 0xffff7000
	v_lshl_add_u64 v[156:157], v[204:205], 0, s[2:3]
	s_mov_b64 s[2:3], 0x1000
	v_lshl_add_u64 v[160:161], v[204:205], 0, s[2:3]
	global_load_dwordx4 v[154:157], v[156:157], off offset:-3072
	global_load_dwordx4 v[158:161], v[160:161], off offset:-3072
.Lp2_nov:
	ds_read_b64_tr_b16 v[70:71], v243 offset:2048
	ds_read_b64_tr_b16 v[72:73], v244 offset:2048
	s_setprio 1
	s_waitcnt lgkmcnt(0)
	v_mfma_f32_32x32x16_bf16 v[50:65], v[70:73], v[162:165], v[50:65]
	v_mfma_f32_32x32x16_bf16 v[18:33], v[70:73], v[74:77], v[18:33]
	s_setprio 0
	ds_read_b64_tr_b16 v[70:71], v245 offset:2048
	ds_read_b64_tr_b16 v[72:73], v246 offset:2048
	s_setprio 1
	s_waitcnt lgkmcnt(0)
	v_mfma_f32_32x32x16_bf16 v[34:49], v[70:73], v[166:169], v[34:49]
	v_mfma_f32_32x32x16_bf16 v[2:17], v[70:73], v[66:69], v[2:17]
	s_setprio 0
	ds_read_b64_tr_b16 v[66:67], v247 offset:2048
	ds_read_b64_tr_b16 v[68:69], v248 offset:2048
	s_setprio 1
	s_waitcnt lgkmcnt(0)
	v_mfma_f32_32x32x16_bf16 v[34:49], v[66:69], v[162:165], v[34:49]
	v_mfma_f32_32x32x16_bf16 v[2:17], v[66:69], v[74:77], v[2:17]
	s_setprio 0
	s_sub_i32 s7, s7, 32
	s_mov_b64 s[2:3], 0x28000
	s_cmp_gt_u32 s6, 16
	v_lshl_add_u64 v[204:205], v[204:205], 0, s[2:3]
	s_cbranch_scc1 .LBB0_711
	s_waitcnt vmcnt(4)
	v_mov_b64_e32 v[78:79], v[138:139]
	v_mov_b64_e32 v[74:75], v[142:143]
	v_mov_b64_e32 v[70:71], v[134:135]
	v_mov_b64_e32 v[66:67], v[130:131]
	v_mov_b64_e32 v[80:81], v[140:141]
	v_mov_b64_e32 v[76:77], v[144:145]
	v_mov_b64_e32 v[72:73], v[136:137]
	v_mov_b64_e32 v[68:69], v[132:133]
	s_mov_b32 s6, s0
	s_branch .LBB0_695
